# hand-written GLU epilogue: bias quads loaded once, z loads 16 tiles deep (was 64 dependent load round trips); same arithmetic
# speedup vs baseline: 1.0125x; 1.0037x over previous
; __device__ __forceinline__ unsigned cvt_pk_bf16(float lo, float hi) { const f32x2_t v = {lo, hi}; const bf16x2_t b = __builtin_convertvector(v, bf16x2_t); return __builtin_bit_cast(unsigned, b); }
; __device__ __forceinline__ float sigmoidf_(float x) { return __builtin_amdgcn_rcpf(1.0f + __expf(-x)); }
;     __device__ __forceinline__ void operator()(const Acc& acc, const Unit& u, int wr, int wc, int fr, int fq) const {
; #pragma unroll
;         for (int ai = 0; ai < 2; ++ai)
; #pragma unroll
;             for (int m = 0; m < 4; ++m) { const int row = u.pm * 256 + ai * 128 + wr * 64 + m * 16 + fr;
; #pragma unroll
;                 for (int bj = 0; bj < 2; ++bj)
; #pragma unroll
;                     for (int n = 0; n < 2; ++n) { const int col = bj * 128 + wc * 32 + n * 16 + fq * 4; const f32x4 a = acc[ai][bj][m][n] + *(const f32x4*)(bglu + col);
;                         const u32x2 zw = *(const u32x2*)(Z + (size_t)row * 256 + col);
;                         const float o0 = bflo(zw.x) * sigmoidf_(a[0]), o1 = bfhi(zw.x) * sigmoidf_(a[1]), o2 = bflo(zw.y) * sigmoidf_(a[2]), o3 = bfhi(zw.y) * sigmoidf_(a[3]);
;                         *(u32x2*)(MIX + (size_t)row * 1024 + 512 + col) = (u32x2){cvt_pk_bf16(o0, o1), cvt_pk_bf16(o2, o3)}; } }
.LBB0_1156:
	s_mov_b64 s[22:23], -1
	s_lshl_b32 s15, s58, 8
	s_add_i32 s15, s15, s52
	v_add_u32_e32 v244, s15, v136
	v_lshl_add_u32 v245, v137, 2, s53
	v_lshlrev_b32_e32 v246, 2, v245
	v_mov_b32_e32 v247, 0
	v_lshl_add_u64 v[130:131], s[10:11], 0, v[246:247]
	global_load_dwordx4 v[144:147], v[130:131], off
	global_load_dwordx4 v[148:151], v[130:131], off offset:64
	global_load_dwordx4 v[152:155], v[130:131], off offset:512
	global_load_dwordx4 v[156:159], v[130:131], off offset:576
	v_lshlrev_b32_e32 v248, 9, v244
	v_lshl_add_u32 v248, v245, 1, v248
	v_mov_b32_e32 v249, 0
	v_lshl_add_u64 v[132:133], s[6:7], 0, v[248:249]
	v_lshlrev_b32_e32 v250, 11, v244
	v_lshl_add_u32 v250, v245, 1, v250
	v_mov_b32_e32 v251, 0
	v_lshl_add_u64 v[140:141], s[4:5], 0, v[250:251]
	s_mov_b32 s66, 0x2000
	s_mov_b32 s67, 0x0
	s_mov_b32 s68, 0xa000
	s_mov_b32 s69, 0x0
	s_mov_b32 s70, 0x8000
	s_mov_b32 s71, 0x0
	s_mov_b32 s98, 0x28000
	s_mov_b32 s99, 0x0
	global_load_dwordx2 v[208:209], v[132:133], off
	global_load_dwordx2 v[210:211], v[132:133], off offset:32
	global_load_dwordx2 v[212:213], v[132:133], off offset:256
	global_load_dwordx2 v[214:215], v[132:133], off offset:288
	v_lshl_add_u64 v[132:133], v[132:133], 0, s[66:67]
	global_load_dwordx2 v[216:217], v[132:133], off
	global_load_dwordx2 v[218:219], v[132:133], off offset:32
	global_load_dwordx2 v[220:221], v[132:133], off offset:256
	global_load_dwordx2 v[222:223], v[132:133], off offset:288
	v_lshl_add_u64 v[132:133], v[132:133], 0, s[66:67]
	global_load_dwordx2 v[224:225], v[132:133], off
	global_load_dwordx2 v[226:227], v[132:133], off offset:32
	global_load_dwordx2 v[228:229], v[132:133], off offset:256
	global_load_dwordx2 v[230:231], v[132:133], off offset:288
	v_lshl_add_u64 v[132:133], v[132:133], 0, s[66:67]
	global_load_dwordx2 v[232:233], v[132:133], off
	global_load_dwordx2 v[234:235], v[132:133], off offset:32
	global_load_dwordx2 v[236:237], v[132:133], off offset:256
	global_load_dwordx2 v[238:239], v[132:133], off offset:288
	v_lshl_add_u64 v[134:135], v[132:133], 0, s[68:69]
	s_waitcnt vmcnt(15)
	v_pk_add_f32 v[126:127], v[126:127], v[146:147]
	v_pk_add_f32 v[124:125], v[124:125], v[144:145]
	v_mul_f32_e32 v124, 0xbfb8aa3b, v124
	v_mul_f32_e32 v125, 0xbfb8aa3b, v125
	v_mul_f32_e32 v126, 0xbfb8aa3b, v126
	v_mul_f32_e32 v127, 0xbfb8aa3b, v127
	v_exp_f32_e32 v124, v124
	v_exp_f32_e32 v125, v125
	v_exp_f32_e32 v126, v126
	v_exp_f32_e32 v127, v127
	v_add_f32_e32 v124, 1.0, v124
	v_add_f32_e32 v125, 1.0, v125
	v_add_f32_e32 v126, 1.0, v126
	v_add_f32_e32 v127, 1.0, v127
	v_rcp_f32_e32 v124, v124
	v_rcp_f32_e32 v125, v125
	v_rcp_f32_e32 v126, v126
	v_rcp_f32_e32 v127, v127
	v_lshlrev_b32_e32 v240, 16, v208
	v_and_b32_e32 v241, 0xffff0000, v208
	v_lshlrev_b32_e32 v242, 16, v209
	v_and_b32_e32 v243, 0xffff0000, v209
	v_pk_mul_f32 v[124:125], v[124:125], v[240:241]
	v_pk_mul_f32 v[126:127], v[126:127], v[242:243]
	v_cvt_pk_bf16_f32 v124, v124, v125
	v_cvt_pk_bf16_f32 v125, v126, v127
	global_store_dwordx2 v[140:141], v[124:125], off offset:1024
	global_load_dwordx2 v[208:209], v[134:135], off
	s_waitcnt vmcnt(16)
	v_pk_add_f32 v[122:123], v[122:123], v[150:151]
	v_pk_add_f32 v[120:121], v[120:121], v[148:149]
	v_mul_f32_e32 v120, 0xbfb8aa3b, v120
	v_mul_f32_e32 v121, 0xbfb8aa3b, v121
	v_mul_f32_e32 v122, 0xbfb8aa3b, v122
	v_mul_f32_e32 v123, 0xbfb8aa3b, v123
	v_exp_f32_e32 v120, v120
	v_exp_f32_e32 v121, v121
	v_exp_f32_e32 v122, v122
	v_exp_f32_e32 v123, v123
	v_add_f32_e32 v120, 1.0, v120
	v_add_f32_e32 v121, 1.0, v121
	v_add_f32_e32 v122, 1.0, v122
	v_add_f32_e32 v123, 1.0, v123
	v_rcp_f32_e32 v120, v120
	v_rcp_f32_e32 v121, v121
	v_rcp_f32_e32 v122, v122
	v_rcp_f32_e32 v123, v123
	v_lshlrev_b32_e32 v240, 16, v210
	v_and_b32_e32 v241, 0xffff0000, v210
	v_lshlrev_b32_e32 v242, 16, v211
	v_and_b32_e32 v243, 0xffff0000, v211
	v_pk_mul_f32 v[120:121], v[120:121], v[240:241]
	v_pk_mul_f32 v[122:123], v[122:123], v[242:243]
	v_cvt_pk_bf16_f32 v120, v120, v121
	v_cvt_pk_bf16_f32 v121, v122, v123
	global_store_dwordx2 v[140:141], v[120:121], off offset:1056
	global_load_dwordx2 v[210:211], v[134:135], off offset:32
	s_waitcnt vmcnt(17)
	v_pk_add_f32 v[118:119], v[118:119], v[154:155]
	v_pk_add_f32 v[116:117], v[116:117], v[152:153]
	v_mul_f32_e32 v116, 0xbfb8aa3b, v116
	v_mul_f32_e32 v117, 0xbfb8aa3b, v117
	v_mul_f32_e32 v118, 0xbfb8aa3b, v118
	v_mul_f32_e32 v119, 0xbfb8aa3b, v119
	v_exp_f32_e32 v116, v116
	v_exp_f32_e32 v117, v117
	v_exp_f32_e32 v118, v118
	v_exp_f32_e32 v119, v119
	v_add_f32_e32 v116, 1.0, v116
	v_add_f32_e32 v117, 1.0, v117
	v_add_f32_e32 v118, 1.0, v118
	v_add_f32_e32 v119, 1.0, v119
	v_rcp_f32_e32 v116, v116
	v_rcp_f32_e32 v117, v117
	v_rcp_f32_e32 v118, v118
	v_rcp_f32_e32 v119, v119
	v_lshlrev_b32_e32 v240, 16, v212
	v_and_b32_e32 v241, 0xffff0000, v212
	v_lshlrev_b32_e32 v242, 16, v213
	v_and_b32_e32 v243, 0xffff0000, v213
	v_pk_mul_f32 v[116:117], v[116:117], v[240:241]
	v_pk_mul_f32 v[118:119], v[118:119], v[242:243]
	v_cvt_pk_bf16_f32 v116, v116, v117
	v_cvt_pk_bf16_f32 v117, v118, v119
	global_store_dwordx2 v[140:141], v[116:117], off offset:1280
	global_load_dwordx2 v[212:213], v[134:135], off offset:256
	s_waitcnt vmcnt(18)
; __device__ __forceinline__ unsigned cvt_pk_bf16(float lo, float hi) { const f32x2_t v = {lo, hi}; const bf16x2_t b = __builtin_convertvector(v, bf16x2_t); return __builtin_bit_cast(unsigned, b); }
; __device__ __forceinline__ float sigmoidf_(float x) { return __builtin_amdgcn_rcpf(1.0f + __expf(-x)); }
;     __device__ __forceinline__ void operator()(const Acc& acc, const Unit& u, int wr, int wc, int fr, int fq) const {
; #pragma unroll
;         for (int ai = 0; ai < 2; ++ai)
; #pragma unroll
;             for (int m = 0; m < 4; ++m) { const int row = u.pm * 256 + ai * 128 + wr * 64 + m * 16 + fr;
; #pragma unroll
;                 for (int bj = 0; bj < 2; ++bj)
; #pragma unroll
;                     for (int n = 0; n < 2; ++n) { const int col = bj * 128 + wc * 32 + n * 16 + fq * 4; const f32x4 a = acc[ai][bj][m][n] + *(const f32x4*)(bglu + col);
;                         const u32x2 zw = *(const u32x2*)(Z + (size_t)row * 256 + col);
;                         const float o0 = bflo(zw.x) * sigmoidf_(a[0]), o1 = bfhi(zw.x) * sigmoidf_(a[1]), o2 = bflo(zw.y) * sigmoidf_(a[2]), o3 = bfhi(zw.y) * sigmoidf_(a[3]);
;                         *(u32x2*)(MIX + (size_t)row * 1024 + 512 + col) = (u32x2){cvt_pk_bf16(o0, o1), cvt_pk_bf16(o2, o3)}; } }
	v_pk_add_f32 v[114:115], v[114:115], v[158:159]
	v_pk_add_f32 v[112:113], v[112:113], v[156:157]
	v_mul_f32_e32 v112, 0xbfb8aa3b, v112
	v_mul_f32_e32 v113, 0xbfb8aa3b, v113
	v_mul_f32_e32 v114, 0xbfb8aa3b, v114
	v_mul_f32_e32 v115, 0xbfb8aa3b, v115
	v_exp_f32_e32 v112, v112
	v_exp_f32_e32 v113, v113
	v_exp_f32_e32 v114, v114
	v_exp_f32_e32 v115, v115
	v_add_f32_e32 v112, 1.0, v112
	v_add_f32_e32 v113, 1.0, v113
	v_add_f32_e32 v114, 1.0, v114
	v_add_f32_e32 v115, 1.0, v115
	v_rcp_f32_e32 v112, v112
	v_rcp_f32_e32 v113, v113
	v_rcp_f32_e32 v114, v114
	v_rcp_f32_e32 v115, v115
	v_lshlrev_b32_e32 v240, 16, v214
	v_and_b32_e32 v241, 0xffff0000, v214
	v_lshlrev_b32_e32 v242, 16, v215
	v_and_b32_e32 v243, 0xffff0000, v215
	v_pk_mul_f32 v[112:113], v[112:113], v[240:241]
	v_pk_mul_f32 v[114:115], v[114:115], v[242:243]
	v_cvt_pk_bf16_f32 v112, v112, v113
	v_cvt_pk_bf16_f32 v113, v114, v115
	global_store_dwordx2 v[140:141], v[112:113], off offset:1312
	global_load_dwordx2 v[214:215], v[134:135], off offset:288
	v_lshl_add_u64 v[140:141], v[140:141], 0, s[70:71]
	v_lshl_add_u64 v[134:135], v[134:135], 0, s[66:67]
	s_waitcnt vmcnt(19)
	v_pk_add_f32 v[110:111], v[110:111], v[146:147]
	v_pk_add_f32 v[108:109], v[108:109], v[144:145]
	v_mul_f32_e32 v108, 0xbfb8aa3b, v108
	v_mul_f32_e32 v109, 0xbfb8aa3b, v109
	v_mul_f32_e32 v110, 0xbfb8aa3b, v110
	v_mul_f32_e32 v111, 0xbfb8aa3b, v111
	v_exp_f32_e32 v108, v108
	v_exp_f32_e32 v109, v109
	v_exp_f32_e32 v110, v110
	v_exp_f32_e32 v111, v111
	v_add_f32_e32 v108, 1.0, v108
	v_add_f32_e32 v109, 1.0, v109
	v_add_f32_e32 v110, 1.0, v110
	v_add_f32_e32 v111, 1.0, v111
	v_rcp_f32_e32 v108, v108
	v_rcp_f32_e32 v109, v109
	v_rcp_f32_e32 v110, v110
	v_rcp_f32_e32 v111, v111
	v_lshlrev_b32_e32 v240, 16, v216
	v_and_b32_e32 v241, 0xffff0000, v216
	v_lshlrev_b32_e32 v242, 16, v217
	v_and_b32_e32 v243, 0xffff0000, v217
	v_pk_mul_f32 v[108:109], v[108:109], v[240:241]
	v_pk_mul_f32 v[110:111], v[110:111], v[242:243]
	v_cvt_pk_bf16_f32 v108, v108, v109
	v_cvt_pk_bf16_f32 v109, v110, v111
	global_store_dwordx2 v[140:141], v[108:109], off offset:1024
	global_load_dwordx2 v[216:217], v[134:135], off
	s_waitcnt vmcnt(20)
	v_pk_add_f32 v[106:107], v[106:107], v[150:151]
	v_pk_add_f32 v[104:105], v[104:105], v[148:149]
	v_mul_f32_e32 v104, 0xbfb8aa3b, v104
	v_mul_f32_e32 v105, 0xbfb8aa3b, v105
	v_mul_f32_e32 v106, 0xbfb8aa3b, v106
	v_mul_f32_e32 v107, 0xbfb8aa3b, v107
	v_exp_f32_e32 v104, v104
	v_exp_f32_e32 v105, v105
	v_exp_f32_e32 v106, v106
	v_exp_f32_e32 v107, v107
	v_add_f32_e32 v104, 1.0, v104
	v_add_f32_e32 v105, 1.0, v105
	v_add_f32_e32 v106, 1.0, v106
	v_add_f32_e32 v107, 1.0, v107
	v_rcp_f32_e32 v104, v104
	v_rcp_f32_e32 v105, v105
	v_rcp_f32_e32 v106, v106
	v_rcp_f32_e32 v107, v107
	v_lshlrev_b32_e32 v240, 16, v218
	v_and_b32_e32 v241, 0xffff0000, v218
	v_lshlrev_b32_e32 v242, 16, v219
	v_and_b32_e32 v243, 0xffff0000, v219
	v_pk_mul_f32 v[104:105], v[104:105], v[240:241]
	v_pk_mul_f32 v[106:107], v[106:107], v[242:243]
	v_cvt_pk_bf16_f32 v104, v104, v105
	v_cvt_pk_bf16_f32 v105, v106, v107
	global_store_dwordx2 v[140:141], v[104:105], off offset:1056
	global_load_dwordx2 v[218:219], v[134:135], off offset:32
	s_waitcnt vmcnt(21)
	v_pk_add_f32 v[102:103], v[102:103], v[154:155]
	v_pk_add_f32 v[100:101], v[100:101], v[152:153]
	v_mul_f32_e32 v100, 0xbfb8aa3b, v100
	v_mul_f32_e32 v101, 0xbfb8aa3b, v101
	v_mul_f32_e32 v102, 0xbfb8aa3b, v102
	v_mul_f32_e32 v103, 0xbfb8aa3b, v103
	v_exp_f32_e32 v100, v100
	v_exp_f32_e32 v101, v101
	v_exp_f32_e32 v102, v102
	v_exp_f32_e32 v103, v103
	v_add_f32_e32 v100, 1.0, v100
	v_add_f32_e32 v101, 1.0, v101
	v_add_f32_e32 v102, 1.0, v102
	v_add_f32_e32 v103, 1.0, v103
	v_rcp_f32_e32 v100, v100
	v_rcp_f32_e32 v101, v101
	v_rcp_f32_e32 v102, v102
	v_rcp_f32_e32 v103, v103
	v_lshlrev_b32_e32 v240, 16, v220
	v_and_b32_e32 v241, 0xffff0000, v220
	v_lshlrev_b32_e32 v242, 16, v221
	v_and_b32_e32 v243, 0xffff0000, v221
	v_pk_mul_f32 v[100:101], v[100:101], v[240:241]
	v_pk_mul_f32 v[102:103], v[102:103], v[242:243]
	v_cvt_pk_bf16_f32 v100, v100, v101
	v_cvt_pk_bf16_f32 v101, v102, v103
	global_store_dwordx2 v[140:141], v[100:101], off offset:1280
	global_load_dwordx2 v[220:221], v[134:135], off offset:256
	s_waitcnt vmcnt(22)
	v_pk_add_f32 v[98:99], v[98:99], v[158:159]
	v_pk_add_f32 v[96:97], v[96:97], v[156:157]
	v_mul_f32_e32 v96, 0xbfb8aa3b, v96
	v_mul_f32_e32 v97, 0xbfb8aa3b, v97
	v_mul_f32_e32 v98, 0xbfb8aa3b, v98
	v_mul_f32_e32 v99, 0xbfb8aa3b, v99
	v_exp_f32_e32 v96, v96
	v_exp_f32_e32 v97, v97
	v_exp_f32_e32 v98, v98
	v_exp_f32_e32 v99, v99
	v_add_f32_e32 v96, 1.0, v96
	v_add_f32_e32 v97, 1.0, v97
	v_add_f32_e32 v98, 1.0, v98
	v_add_f32_e32 v99, 1.0, v99
	v_rcp_f32_e32 v96, v96
	v_rcp_f32_e32 v97, v97
	v_rcp_f32_e32 v98, v98
	v_rcp_f32_e32 v99, v99
	v_lshlrev_b32_e32 v240, 16, v222
	v_and_b32_e32 v241, 0xffff0000, v222
	v_lshlrev_b32_e32 v242, 16, v223
	v_and_b32_e32 v243, 0xffff0000, v223
	v_pk_mul_f32 v[96:97], v[96:97], v[240:241]
	v_pk_mul_f32 v[98:99], v[98:99], v[242:243]
	v_cvt_pk_bf16_f32 v96, v96, v97
	v_cvt_pk_bf16_f32 v97, v98, v99
	global_store_dwordx2 v[140:141], v[96:97], off offset:1312
	global_load_dwordx2 v[222:223], v[134:135], off offset:288
	v_lshl_add_u64 v[140:141], v[140:141], 0, s[70:71]
	v_lshl_add_u64 v[134:135], v[134:135], 0, s[66:67]
	s_waitcnt vmcnt(23)
; __device__ __forceinline__ unsigned cvt_pk_bf16(float lo, float hi) { const f32x2_t v = {lo, hi}; const bf16x2_t b = __builtin_convertvector(v, bf16x2_t); return __builtin_bit_cast(unsigned, b); }
; __device__ __forceinline__ float sigmoidf_(float x) { return __builtin_amdgcn_rcpf(1.0f + __expf(-x)); }
;     __device__ __forceinline__ void operator()(const Acc& acc, const Unit& u, int wr, int wc, int fr, int fq) const {
; #pragma unroll
;         for (int ai = 0; ai < 2; ++ai)
; #pragma unroll
;             for (int m = 0; m < 4; ++m) { const int row = u.pm * 256 + ai * 128 + wr * 64 + m * 16 + fr;
; #pragma unroll
;                 for (int bj = 0; bj < 2; ++bj)
; #pragma unroll
;                     for (int n = 0; n < 2; ++n) { const int col = bj * 128 + wc * 32 + n * 16 + fq * 4; const f32x4 a = acc[ai][bj][m][n] + *(const f32x4*)(bglu + col);
;                         const u32x2 zw = *(const u32x2*)(Z + (size_t)row * 256 + col);
;                         const float o0 = bflo(zw.x) * sigmoidf_(a[0]), o1 = bfhi(zw.x) * sigmoidf_(a[1]), o2 = bflo(zw.y) * sigmoidf_(a[2]), o3 = bfhi(zw.y) * sigmoidf_(a[3]);
;                         *(u32x2*)(MIX + (size_t)row * 1024 + 512 + col) = (u32x2){cvt_pk_bf16(o0, o1), cvt_pk_bf16(o2, o3)}; } }
;     }
	v_pk_add_f32 v[94:95], v[94:95], v[146:147]
	v_pk_add_f32 v[92:93], v[92:93], v[144:145]
	v_mul_f32_e32 v92, 0xbfb8aa3b, v92
	v_mul_f32_e32 v93, 0xbfb8aa3b, v93
	v_mul_f32_e32 v94, 0xbfb8aa3b, v94
	v_mul_f32_e32 v95, 0xbfb8aa3b, v95
	v_exp_f32_e32 v92, v92
	v_exp_f32_e32 v93, v93
	v_exp_f32_e32 v94, v94
	v_exp_f32_e32 v95, v95
	v_add_f32_e32 v92, 1.0, v92
	v_add_f32_e32 v93, 1.0, v93
	v_add_f32_e32 v94, 1.0, v94
	v_add_f32_e32 v95, 1.0, v95
	v_rcp_f32_e32 v92, v92
	v_rcp_f32_e32 v93, v93
	v_rcp_f32_e32 v94, v94
	v_rcp_f32_e32 v95, v95
	v_lshlrev_b32_e32 v240, 16, v224
	v_and_b32_e32 v241, 0xffff0000, v224
	v_lshlrev_b32_e32 v242, 16, v225
	v_and_b32_e32 v243, 0xffff0000, v225
	v_pk_mul_f32 v[92:93], v[92:93], v[240:241]
	v_pk_mul_f32 v[94:95], v[94:95], v[242:243]
	v_cvt_pk_bf16_f32 v92, v92, v93
	v_cvt_pk_bf16_f32 v93, v94, v95
	global_store_dwordx2 v[140:141], v[92:93], off offset:1024
	global_load_dwordx2 v[224:225], v[134:135], off
	s_waitcnt vmcnt(24)
	v_pk_add_f32 v[90:91], v[90:91], v[150:151]
	v_pk_add_f32 v[88:89], v[88:89], v[148:149]
	v_mul_f32_e32 v88, 0xbfb8aa3b, v88
	v_mul_f32_e32 v89, 0xbfb8aa3b, v89
	v_mul_f32_e32 v90, 0xbfb8aa3b, v90
	v_mul_f32_e32 v91, 0xbfb8aa3b, v91
	v_exp_f32_e32 v88, v88
	v_exp_f32_e32 v89, v89
	v_exp_f32_e32 v90, v90
	v_exp_f32_e32 v91, v91
	v_add_f32_e32 v88, 1.0, v88
	v_add_f32_e32 v89, 1.0, v89
	v_add_f32_e32 v90, 1.0, v90
	v_add_f32_e32 v91, 1.0, v91
	v_rcp_f32_e32 v88, v88
	v_rcp_f32_e32 v89, v89
	v_rcp_f32_e32 v90, v90
	v_rcp_f32_e32 v91, v91
	v_lshlrev_b32_e32 v240, 16, v226
	v_and_b32_e32 v241, 0xffff0000, v226
	v_lshlrev_b32_e32 v242, 16, v227
	v_and_b32_e32 v243, 0xffff0000, v227
	v_pk_mul_f32 v[88:89], v[88:89], v[240:241]
	v_pk_mul_f32 v[90:91], v[90:91], v[242:243]
	v_cvt_pk_bf16_f32 v88, v88, v89
	v_cvt_pk_bf16_f32 v89, v90, v91
	global_store_dwordx2 v[140:141], v[88:89], off offset:1056
	global_load_dwordx2 v[226:227], v[134:135], off offset:32
	s_waitcnt vmcnt(25)
	v_pk_add_f32 v[86:87], v[86:87], v[154:155]
	v_pk_add_f32 v[84:85], v[84:85], v[152:153]
	v_mul_f32_e32 v84, 0xbfb8aa3b, v84
	v_mul_f32_e32 v85, 0xbfb8aa3b, v85
	v_mul_f32_e32 v86, 0xbfb8aa3b, v86
	v_mul_f32_e32 v87, 0xbfb8aa3b, v87
	v_exp_f32_e32 v84, v84
	v_exp_f32_e32 v85, v85
	v_exp_f32_e32 v86, v86
	v_exp_f32_e32 v87, v87
	v_add_f32_e32 v84, 1.0, v84
	v_add_f32_e32 v85, 1.0, v85
	v_add_f32_e32 v86, 1.0, v86
	v_add_f32_e32 v87, 1.0, v87
	v_rcp_f32_e32 v84, v84
	v_rcp_f32_e32 v85, v85
	v_rcp_f32_e32 v86, v86
	v_rcp_f32_e32 v87, v87
	v_lshlrev_b32_e32 v240, 16, v228
	v_and_b32_e32 v241, 0xffff0000, v228
	v_lshlrev_b32_e32 v242, 16, v229
	v_and_b32_e32 v243, 0xffff0000, v229
	v_pk_mul_f32 v[84:85], v[84:85], v[240:241]
	v_pk_mul_f32 v[86:87], v[86:87], v[242:243]
	v_cvt_pk_bf16_f32 v84, v84, v85
	v_cvt_pk_bf16_f32 v85, v86, v87
	global_store_dwordx2 v[140:141], v[84:85], off offset:1280
	global_load_dwordx2 v[228:229], v[134:135], off offset:256
	s_waitcnt vmcnt(26)
	v_pk_add_f32 v[82:83], v[82:83], v[158:159]
	v_pk_add_f32 v[80:81], v[80:81], v[156:157]
	v_mul_f32_e32 v80, 0xbfb8aa3b, v80
	v_mul_f32_e32 v81, 0xbfb8aa3b, v81
	v_mul_f32_e32 v82, 0xbfb8aa3b, v82
	v_mul_f32_e32 v83, 0xbfb8aa3b, v83
	v_exp_f32_e32 v80, v80
	v_exp_f32_e32 v81, v81
	v_exp_f32_e32 v82, v82
	v_exp_f32_e32 v83, v83
	v_add_f32_e32 v80, 1.0, v80
	v_add_f32_e32 v81, 1.0, v81
	v_add_f32_e32 v82, 1.0, v82
	v_add_f32_e32 v83, 1.0, v83
	v_rcp_f32_e32 v80, v80
	v_rcp_f32_e32 v81, v81
	v_rcp_f32_e32 v82, v82
	v_rcp_f32_e32 v83, v83
	v_lshlrev_b32_e32 v240, 16, v230
	v_and_b32_e32 v241, 0xffff0000, v230
	v_lshlrev_b32_e32 v242, 16, v231
	v_and_b32_e32 v243, 0xffff0000, v231
	v_pk_mul_f32 v[80:81], v[80:81], v[240:241]
	v_pk_mul_f32 v[82:83], v[82:83], v[242:243]
	v_cvt_pk_bf16_f32 v80, v80, v81
	v_cvt_pk_bf16_f32 v81, v82, v83
	global_store_dwordx2 v[140:141], v[80:81], off offset:1312
	global_load_dwordx2 v[230:231], v[134:135], off offset:288
	v_lshl_add_u64 v[140:141], v[140:141], 0, s[70:71]
	v_lshl_add_u64 v[134:135], v[134:135], 0, s[66:67]
	s_waitcnt vmcnt(27)
	v_pk_add_f32 v[78:79], v[78:79], v[146:147]
	v_pk_add_f32 v[76:77], v[76:77], v[144:145]
	v_mul_f32_e32 v76, 0xbfb8aa3b, v76
	v_mul_f32_e32 v77, 0xbfb8aa3b, v77
	v_mul_f32_e32 v78, 0xbfb8aa3b, v78
	v_mul_f32_e32 v79, 0xbfb8aa3b, v79
	v_exp_f32_e32 v76, v76
	v_exp_f32_e32 v77, v77
	v_exp_f32_e32 v78, v78
	v_exp_f32_e32 v79, v79
	v_add_f32_e32 v76, 1.0, v76
	v_add_f32_e32 v77, 1.0, v77
	v_add_f32_e32 v78, 1.0, v78
	v_add_f32_e32 v79, 1.0, v79
	v_rcp_f32_e32 v76, v76
	v_rcp_f32_e32 v77, v77
	v_rcp_f32_e32 v78, v78
	v_rcp_f32_e32 v79, v79
	v_lshlrev_b32_e32 v240, 16, v232
	v_and_b32_e32 v241, 0xffff0000, v232
	v_lshlrev_b32_e32 v242, 16, v233
	v_and_b32_e32 v243, 0xffff0000, v233
	v_pk_mul_f32 v[76:77], v[76:77], v[240:241]
	v_pk_mul_f32 v[78:79], v[78:79], v[242:243]
	v_cvt_pk_bf16_f32 v76, v76, v77
	v_cvt_pk_bf16_f32 v77, v78, v79
	global_store_dwordx2 v[140:141], v[76:77], off offset:1024
	global_load_dwordx2 v[232:233], v[134:135], off
	s_waitcnt vmcnt(28)
	v_pk_add_f32 v[74:75], v[74:75], v[150:151]
	v_pk_add_f32 v[72:73], v[72:73], v[148:149]
	v_mul_f32_e32 v72, 0xbfb8aa3b, v72
	v_mul_f32_e32 v73, 0xbfb8aa3b, v73
	v_mul_f32_e32 v74, 0xbfb8aa3b, v74
	v_mul_f32_e32 v75, 0xbfb8aa3b, v75
	v_exp_f32_e32 v72, v72
	v_exp_f32_e32 v73, v73
	v_exp_f32_e32 v74, v74
	v_exp_f32_e32 v75, v75
	v_add_f32_e32 v72, 1.0, v72
	v_add_f32_e32 v73, 1.0, v73
	v_add_f32_e32 v74, 1.0, v74
	v_add_f32_e32 v75, 1.0, v75
	v_rcp_f32_e32 v72, v72
	v_rcp_f32_e32 v73, v73
	v_rcp_f32_e32 v74, v74
	v_rcp_f32_e32 v75, v75
	v_lshlrev_b32_e32 v240, 16, v234
	v_and_b32_e32 v241, 0xffff0000, v234
	v_lshlrev_b32_e32 v242, 16, v235
	v_and_b32_e32 v243, 0xffff0000, v235
	v_pk_mul_f32 v[72:73], v[72:73], v[240:241]
	v_pk_mul_f32 v[74:75], v[74:75], v[242:243]
	v_cvt_pk_bf16_f32 v72, v72, v73
	v_cvt_pk_bf16_f32 v73, v74, v75
	global_store_dwordx2 v[140:141], v[72:73], off offset:1056
	global_load_dwordx2 v[234:235], v[134:135], off offset:32
	s_waitcnt vmcnt(29)
; __device__ __forceinline__ unsigned cvt_pk_bf16(float lo, float hi) { const f32x2_t v = {lo, hi}; const bf16x2_t b = __builtin_convertvector(v, bf16x2_t); return __builtin_bit_cast(unsigned, b); }
; __device__ __forceinline__ float sigmoidf_(float x) { return __builtin_amdgcn_rcpf(1.0f + __expf(-x)); }
;     __device__ __forceinline__ void operator()(const Acc& acc, const Unit& u, int wr, int wc, int fr, int fq) const {
; #pragma unroll
;         for (int ai = 0; ai < 2; ++ai)
; #pragma unroll
;             for (int m = 0; m < 4; ++m) { const int row = u.pm * 256 + ai * 128 + wr * 64 + m * 16 + fr;
; #pragma unroll
;                 for (int bj = 0; bj < 2; ++bj)
; #pragma unroll
;                     for (int n = 0; n < 2; ++n) { const int col = bj * 128 + wc * 32 + n * 16 + fq * 4; const f32x4 a = acc[ai][bj][m][n] + *(const f32x4*)(bglu + col);
;                         const u32x2 zw = *(const u32x2*)(Z + (size_t)row * 256 + col);
;                         const float o0 = bflo(zw.x) * sigmoidf_(a[0]), o1 = bfhi(zw.x) * sigmoidf_(a[1]), o2 = bflo(zw.y) * sigmoidf_(a[2]), o3 = bfhi(zw.y) * sigmoidf_(a[3]);
;                         *(u32x2*)(MIX + (size_t)row * 1024 + 512 + col) = (u32x2){cvt_pk_bf16(o0, o1), cvt_pk_bf16(o2, o3)}; } }
;     }
	v_pk_add_f32 v[70:71], v[70:71], v[154:155]
	v_pk_add_f32 v[68:69], v[68:69], v[152:153]
	v_mul_f32_e32 v68, 0xbfb8aa3b, v68
	v_mul_f32_e32 v69, 0xbfb8aa3b, v69
	v_mul_f32_e32 v70, 0xbfb8aa3b, v70
	v_mul_f32_e32 v71, 0xbfb8aa3b, v71
	v_exp_f32_e32 v68, v68
	v_exp_f32_e32 v69, v69
	v_exp_f32_e32 v70, v70
	v_exp_f32_e32 v71, v71
	v_add_f32_e32 v68, 1.0, v68
	v_add_f32_e32 v69, 1.0, v69
	v_add_f32_e32 v70, 1.0, v70
	v_add_f32_e32 v71, 1.0, v71
	v_rcp_f32_e32 v68, v68
	v_rcp_f32_e32 v69, v69
	v_rcp_f32_e32 v70, v70
	v_rcp_f32_e32 v71, v71
	v_lshlrev_b32_e32 v240, 16, v236
	v_and_b32_e32 v241, 0xffff0000, v236
	v_lshlrev_b32_e32 v242, 16, v237
	v_and_b32_e32 v243, 0xffff0000, v237
	v_pk_mul_f32 v[68:69], v[68:69], v[240:241]
	v_pk_mul_f32 v[70:71], v[70:71], v[242:243]
	v_cvt_pk_bf16_f32 v68, v68, v69
	v_cvt_pk_bf16_f32 v69, v70, v71
	global_store_dwordx2 v[140:141], v[68:69], off offset:1280
	global_load_dwordx2 v[236:237], v[134:135], off offset:256
	s_waitcnt vmcnt(30)
	v_pk_add_f32 v[66:67], v[66:67], v[158:159]
	v_pk_add_f32 v[64:65], v[64:65], v[156:157]
	v_mul_f32_e32 v64, 0xbfb8aa3b, v64
	v_mul_f32_e32 v65, 0xbfb8aa3b, v65
	v_mul_f32_e32 v66, 0xbfb8aa3b, v66
	v_mul_f32_e32 v67, 0xbfb8aa3b, v67
	v_exp_f32_e32 v64, v64
	v_exp_f32_e32 v65, v65
	v_exp_f32_e32 v66, v66
	v_exp_f32_e32 v67, v67
	v_add_f32_e32 v64, 1.0, v64
	v_add_f32_e32 v65, 1.0, v65
	v_add_f32_e32 v66, 1.0, v66
	v_add_f32_e32 v67, 1.0, v67
	v_rcp_f32_e32 v64, v64
	v_rcp_f32_e32 v65, v65
	v_rcp_f32_e32 v66, v66
	v_rcp_f32_e32 v67, v67
	v_lshlrev_b32_e32 v240, 16, v238
	v_and_b32_e32 v241, 0xffff0000, v238
	v_lshlrev_b32_e32 v242, 16, v239
	v_and_b32_e32 v243, 0xffff0000, v239
	v_pk_mul_f32 v[64:65], v[64:65], v[240:241]
	v_pk_mul_f32 v[66:67], v[66:67], v[242:243]
	v_cvt_pk_bf16_f32 v64, v64, v65
	v_cvt_pk_bf16_f32 v65, v66, v67
	global_store_dwordx2 v[140:141], v[64:65], off offset:1312
	global_load_dwordx2 v[238:239], v[134:135], off offset:288
	v_lshl_add_u64 v[140:141], v[140:141], 0, s[98:99]
	s_waitcnt vmcnt(30)
	v_pk_add_f32 v[62:63], v[62:63], v[146:147]
	v_pk_add_f32 v[60:61], v[60:61], v[144:145]
	v_mul_f32_e32 v60, 0xbfb8aa3b, v60
	v_mul_f32_e32 v61, 0xbfb8aa3b, v61
	v_mul_f32_e32 v62, 0xbfb8aa3b, v62
	v_mul_f32_e32 v63, 0xbfb8aa3b, v63
	v_exp_f32_e32 v60, v60
	v_exp_f32_e32 v61, v61
	v_exp_f32_e32 v62, v62
	v_exp_f32_e32 v63, v63
	v_add_f32_e32 v60, 1.0, v60
	v_add_f32_e32 v61, 1.0, v61
	v_add_f32_e32 v62, 1.0, v62
	v_add_f32_e32 v63, 1.0, v63
	v_rcp_f32_e32 v60, v60
	v_rcp_f32_e32 v61, v61
	v_rcp_f32_e32 v62, v62
	v_rcp_f32_e32 v63, v63
	v_lshlrev_b32_e32 v240, 16, v208
	v_and_b32_e32 v241, 0xffff0000, v208
	v_lshlrev_b32_e32 v242, 16, v209
	v_and_b32_e32 v243, 0xffff0000, v209
	v_pk_mul_f32 v[60:61], v[60:61], v[240:241]
	v_pk_mul_f32 v[62:63], v[62:63], v[242:243]
	v_cvt_pk_bf16_f32 v60, v60, v61
	v_cvt_pk_bf16_f32 v61, v62, v63
	global_store_dwordx2 v[140:141], v[60:61], off offset:1024
	s_waitcnt vmcnt(29)
	v_pk_add_f32 v[58:59], v[58:59], v[150:151]
	v_pk_add_f32 v[56:57], v[56:57], v[148:149]
	v_mul_f32_e32 v56, 0xbfb8aa3b, v56
	v_mul_f32_e32 v57, 0xbfb8aa3b, v57
	v_mul_f32_e32 v58, 0xbfb8aa3b, v58
	v_mul_f32_e32 v59, 0xbfb8aa3b, v59
	v_exp_f32_e32 v56, v56
	v_exp_f32_e32 v57, v57
	v_exp_f32_e32 v58, v58
	v_exp_f32_e32 v59, v59
	v_add_f32_e32 v56, 1.0, v56
	v_add_f32_e32 v57, 1.0, v57
	v_add_f32_e32 v58, 1.0, v58
	v_add_f32_e32 v59, 1.0, v59
	v_rcp_f32_e32 v56, v56
	v_rcp_f32_e32 v57, v57
	v_rcp_f32_e32 v58, v58
	v_rcp_f32_e32 v59, v59
	v_lshlrev_b32_e32 v240, 16, v210
	v_and_b32_e32 v241, 0xffff0000, v210
	v_lshlrev_b32_e32 v242, 16, v211
	v_and_b32_e32 v243, 0xffff0000, v211
	v_pk_mul_f32 v[56:57], v[56:57], v[240:241]
	v_pk_mul_f32 v[58:59], v[58:59], v[242:243]
	v_cvt_pk_bf16_f32 v56, v56, v57
	v_cvt_pk_bf16_f32 v57, v58, v59
	global_store_dwordx2 v[140:141], v[56:57], off offset:1056
	s_waitcnt vmcnt(28)
	v_pk_add_f32 v[54:55], v[54:55], v[154:155]
	v_pk_add_f32 v[52:53], v[52:53], v[152:153]
	v_mul_f32_e32 v52, 0xbfb8aa3b, v52
	v_mul_f32_e32 v53, 0xbfb8aa3b, v53
	v_mul_f32_e32 v54, 0xbfb8aa3b, v54
	v_mul_f32_e32 v55, 0xbfb8aa3b, v55
	v_exp_f32_e32 v52, v52
	v_exp_f32_e32 v53, v53
	v_exp_f32_e32 v54, v54
	v_exp_f32_e32 v55, v55
	v_add_f32_e32 v52, 1.0, v52
	v_add_f32_e32 v53, 1.0, v53
	v_add_f32_e32 v54, 1.0, v54
	v_add_f32_e32 v55, 1.0, v55
	v_rcp_f32_e32 v52, v52
	v_rcp_f32_e32 v53, v53
	v_rcp_f32_e32 v54, v54
	v_rcp_f32_e32 v55, v55
	v_lshlrev_b32_e32 v240, 16, v212
	v_and_b32_e32 v241, 0xffff0000, v212
	v_lshlrev_b32_e32 v242, 16, v213
	v_and_b32_e32 v243, 0xffff0000, v213
	v_pk_mul_f32 v[52:53], v[52:53], v[240:241]
	v_pk_mul_f32 v[54:55], v[54:55], v[242:243]
	v_cvt_pk_bf16_f32 v52, v52, v53
	v_cvt_pk_bf16_f32 v53, v54, v55
	global_store_dwordx2 v[140:141], v[52:53], off offset:1280
	s_waitcnt vmcnt(27)
	v_pk_add_f32 v[50:51], v[50:51], v[158:159]
	v_pk_add_f32 v[48:49], v[48:49], v[156:157]
	v_mul_f32_e32 v48, 0xbfb8aa3b, v48
	v_mul_f32_e32 v49, 0xbfb8aa3b, v49
	v_mul_f32_e32 v50, 0xbfb8aa3b, v50
	v_mul_f32_e32 v51, 0xbfb8aa3b, v51
	v_exp_f32_e32 v48, v48
	v_exp_f32_e32 v49, v49
	v_exp_f32_e32 v50, v50
	v_exp_f32_e32 v51, v51
	v_add_f32_e32 v48, 1.0, v48
	v_add_f32_e32 v49, 1.0, v49
	v_add_f32_e32 v50, 1.0, v50
	v_add_f32_e32 v51, 1.0, v51
	v_rcp_f32_e32 v48, v48
	v_rcp_f32_e32 v49, v49
	v_rcp_f32_e32 v50, v50
	v_rcp_f32_e32 v51, v51
	v_lshlrev_b32_e32 v240, 16, v214
	v_and_b32_e32 v241, 0xffff0000, v214
	v_lshlrev_b32_e32 v242, 16, v215
	v_and_b32_e32 v243, 0xffff0000, v215
	v_pk_mul_f32 v[48:49], v[48:49], v[240:241]
	v_pk_mul_f32 v[50:51], v[50:51], v[242:243]
	v_cvt_pk_bf16_f32 v48, v48, v49
	v_cvt_pk_bf16_f32 v49, v50, v51
	global_store_dwordx2 v[140:141], v[48:49], off offset:1312
	v_lshl_add_u64 v[140:141], v[140:141], 0, s[70:71]
	s_waitcnt vmcnt(26)
; __device__ __forceinline__ unsigned cvt_pk_bf16(float lo, float hi) { const f32x2_t v = {lo, hi}; const bf16x2_t b = __builtin_convertvector(v, bf16x2_t); return __builtin_bit_cast(unsigned, b); }
; __device__ __forceinline__ float sigmoidf_(float x) { return __builtin_amdgcn_rcpf(1.0f + __expf(-x)); }
;     __device__ __forceinline__ void operator()(const Acc& acc, const Unit& u, int wr, int wc, int fr, int fq) const {
; #pragma unroll
;         for (int ai = 0; ai < 2; ++ai)
; #pragma unroll
;             for (int m = 0; m < 4; ++m) { const int row = u.pm * 256 + ai * 128 + wr * 64 + m * 16 + fr;
; #pragma unroll
;                 for (int bj = 0; bj < 2; ++bj)
; #pragma unroll
;                     for (int n = 0; n < 2; ++n) { const int col = bj * 128 + wc * 32 + n * 16 + fq * 4; const f32x4 a = acc[ai][bj][m][n] + *(const f32x4*)(bglu + col);
;                         const u32x2 zw = *(const u32x2*)(Z + (size_t)row * 256 + col);
;                         const float o0 = bflo(zw.x) * sigmoidf_(a[0]), o1 = bfhi(zw.x) * sigmoidf_(a[1]), o2 = bflo(zw.y) * sigmoidf_(a[2]), o3 = bfhi(zw.y) * sigmoidf_(a[3]);
;                         *(u32x2*)(MIX + (size_t)row * 1024 + 512 + col) = (u32x2){cvt_pk_bf16(o0, o1), cvt_pk_bf16(o2, o3)}; } }
;     }
	v_pk_add_f32 v[46:47], v[46:47], v[146:147]
	v_pk_add_f32 v[44:45], v[44:45], v[144:145]
	v_mul_f32_e32 v44, 0xbfb8aa3b, v44
	v_mul_f32_e32 v45, 0xbfb8aa3b, v45
	v_mul_f32_e32 v46, 0xbfb8aa3b, v46
	v_mul_f32_e32 v47, 0xbfb8aa3b, v47
	v_exp_f32_e32 v44, v44
	v_exp_f32_e32 v45, v45
	v_exp_f32_e32 v46, v46
	v_exp_f32_e32 v47, v47
	v_add_f32_e32 v44, 1.0, v44
	v_add_f32_e32 v45, 1.0, v45
	v_add_f32_e32 v46, 1.0, v46
	v_add_f32_e32 v47, 1.0, v47
	v_rcp_f32_e32 v44, v44
	v_rcp_f32_e32 v45, v45
	v_rcp_f32_e32 v46, v46
	v_rcp_f32_e32 v47, v47
	v_lshlrev_b32_e32 v240, 16, v216
	v_and_b32_e32 v241, 0xffff0000, v216
	v_lshlrev_b32_e32 v242, 16, v217
	v_and_b32_e32 v243, 0xffff0000, v217
	v_pk_mul_f32 v[44:45], v[44:45], v[240:241]
	v_pk_mul_f32 v[46:47], v[46:47], v[242:243]
	v_cvt_pk_bf16_f32 v44, v44, v45
	v_cvt_pk_bf16_f32 v45, v46, v47
	global_store_dwordx2 v[140:141], v[44:45], off offset:1024
	s_waitcnt vmcnt(25)
	v_pk_add_f32 v[42:43], v[42:43], v[150:151]
	v_pk_add_f32 v[40:41], v[40:41], v[148:149]
	v_mul_f32_e32 v40, 0xbfb8aa3b, v40
	v_mul_f32_e32 v41, 0xbfb8aa3b, v41
	v_mul_f32_e32 v42, 0xbfb8aa3b, v42
	v_mul_f32_e32 v43, 0xbfb8aa3b, v43
	v_exp_f32_e32 v40, v40
	v_exp_f32_e32 v41, v41
	v_exp_f32_e32 v42, v42
	v_exp_f32_e32 v43, v43
	v_add_f32_e32 v40, 1.0, v40
	v_add_f32_e32 v41, 1.0, v41
	v_add_f32_e32 v42, 1.0, v42
	v_add_f32_e32 v43, 1.0, v43
	v_rcp_f32_e32 v40, v40
	v_rcp_f32_e32 v41, v41
	v_rcp_f32_e32 v42, v42
	v_rcp_f32_e32 v43, v43
	v_lshlrev_b32_e32 v240, 16, v218
	v_and_b32_e32 v241, 0xffff0000, v218
	v_lshlrev_b32_e32 v242, 16, v219
	v_and_b32_e32 v243, 0xffff0000, v219
	v_pk_mul_f32 v[40:41], v[40:41], v[240:241]
	v_pk_mul_f32 v[42:43], v[42:43], v[242:243]
	v_cvt_pk_bf16_f32 v40, v40, v41
	v_cvt_pk_bf16_f32 v41, v42, v43
	global_store_dwordx2 v[140:141], v[40:41], off offset:1056
	s_waitcnt vmcnt(24)
	v_pk_add_f32 v[38:39], v[38:39], v[154:155]
	v_pk_add_f32 v[36:37], v[36:37], v[152:153]
	v_mul_f32_e32 v36, 0xbfb8aa3b, v36
	v_mul_f32_e32 v37, 0xbfb8aa3b, v37
	v_mul_f32_e32 v38, 0xbfb8aa3b, v38
	v_mul_f32_e32 v39, 0xbfb8aa3b, v39
	v_exp_f32_e32 v36, v36
	v_exp_f32_e32 v37, v37
	v_exp_f32_e32 v38, v38
	v_exp_f32_e32 v39, v39
	v_add_f32_e32 v36, 1.0, v36
	v_add_f32_e32 v37, 1.0, v37
	v_add_f32_e32 v38, 1.0, v38
	v_add_f32_e32 v39, 1.0, v39
	v_rcp_f32_e32 v36, v36
	v_rcp_f32_e32 v37, v37
	v_rcp_f32_e32 v38, v38
	v_rcp_f32_e32 v39, v39
	v_lshlrev_b32_e32 v240, 16, v220
	v_and_b32_e32 v241, 0xffff0000, v220
	v_lshlrev_b32_e32 v242, 16, v221
	v_and_b32_e32 v243, 0xffff0000, v221
	v_pk_mul_f32 v[36:37], v[36:37], v[240:241]
	v_pk_mul_f32 v[38:39], v[38:39], v[242:243]
	v_cvt_pk_bf16_f32 v36, v36, v37
	v_cvt_pk_bf16_f32 v37, v38, v39
	global_store_dwordx2 v[140:141], v[36:37], off offset:1280
	s_waitcnt vmcnt(23)
	v_pk_add_f32 v[34:35], v[34:35], v[158:159]
	v_pk_add_f32 v[32:33], v[32:33], v[156:157]
	v_mul_f32_e32 v32, 0xbfb8aa3b, v32
	v_mul_f32_e32 v33, 0xbfb8aa3b, v33
	v_mul_f32_e32 v34, 0xbfb8aa3b, v34
	v_mul_f32_e32 v35, 0xbfb8aa3b, v35
	v_exp_f32_e32 v32, v32
	v_exp_f32_e32 v33, v33
	v_exp_f32_e32 v34, v34
	v_exp_f32_e32 v35, v35
	v_add_f32_e32 v32, 1.0, v32
	v_add_f32_e32 v33, 1.0, v33
	v_add_f32_e32 v34, 1.0, v34
	v_add_f32_e32 v35, 1.0, v35
	v_rcp_f32_e32 v32, v32
	v_rcp_f32_e32 v33, v33
	v_rcp_f32_e32 v34, v34
	v_rcp_f32_e32 v35, v35
	v_lshlrev_b32_e32 v240, 16, v222
	v_and_b32_e32 v241, 0xffff0000, v222
	v_lshlrev_b32_e32 v242, 16, v223
	v_and_b32_e32 v243, 0xffff0000, v223
	v_pk_mul_f32 v[32:33], v[32:33], v[240:241]
	v_pk_mul_f32 v[34:35], v[34:35], v[242:243]
	v_cvt_pk_bf16_f32 v32, v32, v33
	v_cvt_pk_bf16_f32 v33, v34, v35
	global_store_dwordx2 v[140:141], v[32:33], off offset:1312
	v_lshl_add_u64 v[140:141], v[140:141], 0, s[70:71]
	s_waitcnt vmcnt(22)
	v_pk_add_f32 v[30:31], v[30:31], v[146:147]
	v_pk_add_f32 v[28:29], v[28:29], v[144:145]
	v_mul_f32_e32 v28, 0xbfb8aa3b, v28
	v_mul_f32_e32 v29, 0xbfb8aa3b, v29
	v_mul_f32_e32 v30, 0xbfb8aa3b, v30
	v_mul_f32_e32 v31, 0xbfb8aa3b, v31
	v_exp_f32_e32 v28, v28
	v_exp_f32_e32 v29, v29
	v_exp_f32_e32 v30, v30
	v_exp_f32_e32 v31, v31
	v_add_f32_e32 v28, 1.0, v28
	v_add_f32_e32 v29, 1.0, v29
	v_add_f32_e32 v30, 1.0, v30
	v_add_f32_e32 v31, 1.0, v31
	v_rcp_f32_e32 v28, v28
	v_rcp_f32_e32 v29, v29
	v_rcp_f32_e32 v30, v30
	v_rcp_f32_e32 v31, v31
	v_lshlrev_b32_e32 v240, 16, v224
	v_and_b32_e32 v241, 0xffff0000, v224
	v_lshlrev_b32_e32 v242, 16, v225
	v_and_b32_e32 v243, 0xffff0000, v225
	v_pk_mul_f32 v[28:29], v[28:29], v[240:241]
	v_pk_mul_f32 v[30:31], v[30:31], v[242:243]
	v_cvt_pk_bf16_f32 v28, v28, v29
	v_cvt_pk_bf16_f32 v29, v30, v31
	global_store_dwordx2 v[140:141], v[28:29], off offset:1024
	s_waitcnt vmcnt(21)
	v_pk_add_f32 v[26:27], v[26:27], v[150:151]
	v_pk_add_f32 v[24:25], v[24:25], v[148:149]
	v_mul_f32_e32 v24, 0xbfb8aa3b, v24
	v_mul_f32_e32 v25, 0xbfb8aa3b, v25
	v_mul_f32_e32 v26, 0xbfb8aa3b, v26
	v_mul_f32_e32 v27, 0xbfb8aa3b, v27
	v_exp_f32_e32 v24, v24
	v_exp_f32_e32 v25, v25
	v_exp_f32_e32 v26, v26
	v_exp_f32_e32 v27, v27
	v_add_f32_e32 v24, 1.0, v24
	v_add_f32_e32 v25, 1.0, v25
	v_add_f32_e32 v26, 1.0, v26
	v_add_f32_e32 v27, 1.0, v27
	v_rcp_f32_e32 v24, v24
	v_rcp_f32_e32 v25, v25
	v_rcp_f32_e32 v26, v26
	v_rcp_f32_e32 v27, v27
	v_lshlrev_b32_e32 v240, 16, v226
	v_and_b32_e32 v241, 0xffff0000, v226
	v_lshlrev_b32_e32 v242, 16, v227
	v_and_b32_e32 v243, 0xffff0000, v227
	v_pk_mul_f32 v[24:25], v[24:25], v[240:241]
	v_pk_mul_f32 v[26:27], v[26:27], v[242:243]
	v_cvt_pk_bf16_f32 v24, v24, v25
	v_cvt_pk_bf16_f32 v25, v26, v27
	global_store_dwordx2 v[140:141], v[24:25], off offset:1056
	s_waitcnt vmcnt(20)
; __device__ __forceinline__ unsigned cvt_pk_bf16(float lo, float hi) { const f32x2_t v = {lo, hi}; const bf16x2_t b = __builtin_convertvector(v, bf16x2_t); return __builtin_bit_cast(unsigned, b); }
; __device__ __forceinline__ float sigmoidf_(float x) { return __builtin_amdgcn_rcpf(1.0f + __expf(-x)); }
; #define PG8_BAR __builtin_amdgcn_s_barrier()
; template <class Epi, bool ALIGN_EPI>
; __device__ __forceinline__ void gemm_phase(LAS unsigned char* lds, const Gemm g, const Order& S, const Epi& E, const int wave_id) {
;     ...
;         if (!has_next) break;
; #pragma unroll
;         for (int a = 0; a < 2; ++a)
; #pragma unroll
;             for (int b = 0; b < 2; ++b)
; #pragma unroll
;                 for (int m = 0; m < 4; ++m)
; #pragma unroll
;                     for (int n = 0; n < 2; ++n) acc[a][b][m][n] = (f32x4){0.f, 0.f, 0.f, 0.f};
;         cur = nxt; cA = nA; cB = nB; ++ui;
;         if constexpr (ALIGN_EPI) { if (wr == 1) PG8_BAR; }
;     __device__ __forceinline__ void operator()(const Acc& acc, const Unit& u, int wr, int wc, int fr, int fq) const {
;     ...
;                     for (int n = 0; n < 2; ++n) { const int col = bj * 128 + wc * 32 + n * 16 + fq * 4; const f32x4 a = acc[ai][bj][m][n] + *(const f32x4*)(bglu + col);
;                         const u32x2 zw = *(const u32x2*)(Z + (size_t)row * 256 + col);
;                         const float o0 = bflo(zw.x) * sigmoidf_(a[0]), o1 = bfhi(zw.x) * sigmoidf_(a[1]), o2 = bflo(zw.y) * sigmoidf_(a[2]), o3 = bfhi(zw.y) * sigmoidf_(a[3]);
;                         *(u32x2*)(MIX + (size_t)row * 1024 + 512 + col) = (u32x2){cvt_pk_bf16(o0, o1), cvt_pk_bf16(o2, o3)}; } }
	v_pk_add_f32 v[22:23], v[22:23], v[154:155]
	v_pk_add_f32 v[20:21], v[20:21], v[152:153]
	v_mul_f32_e32 v20, 0xbfb8aa3b, v20
	v_mul_f32_e32 v21, 0xbfb8aa3b, v21
	v_mul_f32_e32 v22, 0xbfb8aa3b, v22
	v_mul_f32_e32 v23, 0xbfb8aa3b, v23
	v_exp_f32_e32 v20, v20
	v_exp_f32_e32 v21, v21
	v_exp_f32_e32 v22, v22
	v_exp_f32_e32 v23, v23
	v_add_f32_e32 v20, 1.0, v20
	v_add_f32_e32 v21, 1.0, v21
	v_add_f32_e32 v22, 1.0, v22
	v_add_f32_e32 v23, 1.0, v23
	v_rcp_f32_e32 v20, v20
	v_rcp_f32_e32 v21, v21
	v_rcp_f32_e32 v22, v22
	v_rcp_f32_e32 v23, v23
	v_lshlrev_b32_e32 v240, 16, v228
	v_and_b32_e32 v241, 0xffff0000, v228
	v_lshlrev_b32_e32 v242, 16, v229
	v_and_b32_e32 v243, 0xffff0000, v229
	v_pk_mul_f32 v[20:21], v[20:21], v[240:241]
	v_pk_mul_f32 v[22:23], v[22:23], v[242:243]
	v_cvt_pk_bf16_f32 v20, v20, v21
	v_cvt_pk_bf16_f32 v21, v22, v23
	global_store_dwordx2 v[140:141], v[20:21], off offset:1280
	s_waitcnt vmcnt(19)
	v_pk_add_f32 v[18:19], v[18:19], v[158:159]
	v_pk_add_f32 v[16:17], v[16:17], v[156:157]
	v_mul_f32_e32 v16, 0xbfb8aa3b, v16
	v_mul_f32_e32 v17, 0xbfb8aa3b, v17
	v_mul_f32_e32 v18, 0xbfb8aa3b, v18
	v_mul_f32_e32 v19, 0xbfb8aa3b, v19
	v_exp_f32_e32 v16, v16
	v_exp_f32_e32 v17, v17
	v_exp_f32_e32 v18, v18
	v_exp_f32_e32 v19, v19
	v_add_f32_e32 v16, 1.0, v16
	v_add_f32_e32 v17, 1.0, v17
	v_add_f32_e32 v18, 1.0, v18
	v_add_f32_e32 v19, 1.0, v19
	v_rcp_f32_e32 v16, v16
	v_rcp_f32_e32 v17, v17
	v_rcp_f32_e32 v18, v18
	v_rcp_f32_e32 v19, v19
	v_lshlrev_b32_e32 v240, 16, v230
	v_and_b32_e32 v241, 0xffff0000, v230
	v_lshlrev_b32_e32 v242, 16, v231
	v_and_b32_e32 v243, 0xffff0000, v231
	v_pk_mul_f32 v[16:17], v[16:17], v[240:241]
	v_pk_mul_f32 v[18:19], v[18:19], v[242:243]
	v_cvt_pk_bf16_f32 v16, v16, v17
	v_cvt_pk_bf16_f32 v17, v18, v19
	global_store_dwordx2 v[140:141], v[16:17], off offset:1312
	v_lshl_add_u64 v[140:141], v[140:141], 0, s[70:71]
	s_waitcnt vmcnt(18)
	v_pk_add_f32 v[14:15], v[14:15], v[146:147]
	v_pk_add_f32 v[12:13], v[12:13], v[144:145]
	v_mul_f32_e32 v12, 0xbfb8aa3b, v12
	v_mul_f32_e32 v13, 0xbfb8aa3b, v13
	v_mul_f32_e32 v14, 0xbfb8aa3b, v14
	v_mul_f32_e32 v15, 0xbfb8aa3b, v15
	v_exp_f32_e32 v12, v12
	v_exp_f32_e32 v13, v13
	v_exp_f32_e32 v14, v14
	v_exp_f32_e32 v15, v15
	v_add_f32_e32 v12, 1.0, v12
	v_add_f32_e32 v13, 1.0, v13
	v_add_f32_e32 v14, 1.0, v14
	v_add_f32_e32 v15, 1.0, v15
	v_rcp_f32_e32 v12, v12
	v_rcp_f32_e32 v13, v13
	v_rcp_f32_e32 v14, v14
	v_rcp_f32_e32 v15, v15
	v_lshlrev_b32_e32 v240, 16, v232
	v_and_b32_e32 v241, 0xffff0000, v232
	v_lshlrev_b32_e32 v242, 16, v233
	v_and_b32_e32 v243, 0xffff0000, v233
	v_pk_mul_f32 v[12:13], v[12:13], v[240:241]
	v_pk_mul_f32 v[14:15], v[14:15], v[242:243]
	v_cvt_pk_bf16_f32 v12, v12, v13
	v_cvt_pk_bf16_f32 v13, v14, v15
	global_store_dwordx2 v[140:141], v[12:13], off offset:1024
	s_waitcnt vmcnt(17)
	v_pk_add_f32 v[10:11], v[10:11], v[150:151]
	v_pk_add_f32 v[8:9], v[8:9], v[148:149]
	v_mul_f32_e32 v8, 0xbfb8aa3b, v8
	v_mul_f32_e32 v9, 0xbfb8aa3b, v9
	v_mul_f32_e32 v10, 0xbfb8aa3b, v10
	v_mul_f32_e32 v11, 0xbfb8aa3b, v11
	v_exp_f32_e32 v8, v8
	v_exp_f32_e32 v9, v9
	v_exp_f32_e32 v10, v10
	v_exp_f32_e32 v11, v11
	v_add_f32_e32 v8, 1.0, v8
	v_add_f32_e32 v9, 1.0, v9
	v_add_f32_e32 v10, 1.0, v10
	v_add_f32_e32 v11, 1.0, v11
	v_rcp_f32_e32 v8, v8
	v_rcp_f32_e32 v9, v9
	v_rcp_f32_e32 v10, v10
	v_rcp_f32_e32 v11, v11
	v_lshlrev_b32_e32 v240, 16, v234
	v_and_b32_e32 v241, 0xffff0000, v234
	v_lshlrev_b32_e32 v242, 16, v235
	v_and_b32_e32 v243, 0xffff0000, v235
	v_pk_mul_f32 v[8:9], v[8:9], v[240:241]
	v_pk_mul_f32 v[10:11], v[10:11], v[242:243]
	v_cvt_pk_bf16_f32 v8, v8, v9
	v_cvt_pk_bf16_f32 v9, v10, v11
	global_store_dwordx2 v[140:141], v[8:9], off offset:1056
	s_waitcnt vmcnt(16)
	v_pk_add_f32 v[6:7], v[6:7], v[154:155]
	v_pk_add_f32 v[4:5], v[4:5], v[152:153]
	v_mul_f32_e32 v4, 0xbfb8aa3b, v4
	v_mul_f32_e32 v5, 0xbfb8aa3b, v5
	v_mul_f32_e32 v6, 0xbfb8aa3b, v6
	v_mul_f32_e32 v7, 0xbfb8aa3b, v7
	v_exp_f32_e32 v4, v4
	v_exp_f32_e32 v5, v5
	v_exp_f32_e32 v6, v6
	v_exp_f32_e32 v7, v7
	v_add_f32_e32 v4, 1.0, v4
	v_add_f32_e32 v5, 1.0, v5
	v_add_f32_e32 v6, 1.0, v6
	v_add_f32_e32 v7, 1.0, v7
	v_rcp_f32_e32 v4, v4
	v_rcp_f32_e32 v5, v5
	v_rcp_f32_e32 v6, v6
	v_rcp_f32_e32 v7, v7
	v_lshlrev_b32_e32 v240, 16, v236
	v_and_b32_e32 v241, 0xffff0000, v236
	v_lshlrev_b32_e32 v242, 16, v237
	v_and_b32_e32 v243, 0xffff0000, v237
	v_pk_mul_f32 v[4:5], v[4:5], v[240:241]
	v_pk_mul_f32 v[6:7], v[6:7], v[242:243]
	v_cvt_pk_bf16_f32 v4, v4, v5
	v_cvt_pk_bf16_f32 v5, v6, v7
	global_store_dwordx2 v[140:141], v[4:5], off offset:1280
	s_waitcnt vmcnt(15)
	v_pk_add_f32 v[2:3], v[2:3], v[158:159]
	v_pk_add_f32 v[0:1], v[0:1], v[156:157]
	v_mul_f32_e32 v0, 0xbfb8aa3b, v0
	v_mul_f32_e32 v1, 0xbfb8aa3b, v1
	v_mul_f32_e32 v2, 0xbfb8aa3b, v2
	v_mul_f32_e32 v3, 0xbfb8aa3b, v3
	v_exp_f32_e32 v0, v0
	v_exp_f32_e32 v1, v1
	v_exp_f32_e32 v2, v2
	v_exp_f32_e32 v3, v3
	v_add_f32_e32 v0, 1.0, v0
	v_add_f32_e32 v1, 1.0, v1
	v_add_f32_e32 v2, 1.0, v2
	v_add_f32_e32 v3, 1.0, v3
	v_rcp_f32_e32 v0, v0
	v_rcp_f32_e32 v1, v1
	v_rcp_f32_e32 v2, v2
	v_rcp_f32_e32 v3, v3
	v_lshlrev_b32_e32 v240, 16, v238
	v_and_b32_e32 v241, 0xffff0000, v238
	v_lshlrev_b32_e32 v242, 16, v239
	v_and_b32_e32 v243, 0xffff0000, v239
	v_pk_mul_f32 v[0:1], v[0:1], v[240:241]
	v_pk_mul_f32 v[2:3], v[2:3], v[242:243]
	v_cvt_pk_bf16_f32 v0, v0, v1
	v_cvt_pk_bf16_f32 v1, v2, v3
	global_store_dwordx2 v[140:141], v[0:1], off offset:1312
	s_andn2_b64 vcc, exec, s[0:1]
	s_cbranch_vccnz .LBB0_1145
	s_andn2_b64 vcc, exec, s[8:9]
	s_cbranch_vccnz .LBB0_1144
	s_barrier
	s_branch .LBB0_1144
